# attention main loop: the seven counted lgkmcnt waits per step in front of the Q.K^T MFMAs removed (their K fragments were drained by the lgkmcnt(0) in front of the previous barrier; only the V transpo
# speedup vs baseline: 1.0027x; 1.0027x over previous
.LBB0_1547:
	v_add_u32_e32 v0, s8, v221
	ds_read_b64_tr_b16 v[192:193], v0 offset:24576
	ds_read_b64_tr_b16 v[194:195], v0 offset:25088
	v_mfma_f32_32x32x16_bf16 v[112:127], v[188:191], v[148:151], v[48:63]
	v_add_f32_e32 v2, v80, v81
	v_add_f32_e32 v2, v82, v2
	v_add_f32_e32 v2, v83, v2
	v_add_f32_e32 v2, v84, v2
	v_add_f32_e32 v2, v85, v2
	v_cvt_pk_bf16_f32 v156, v80, v81
	v_cvt_pk_bf16_f32 v157, v82, v83
	ds_read_b64_tr_b16 v[188:189], v0 offset:28672
	ds_read_b64_tr_b16 v[190:191], v0 offset:29184
	v_mfma_f32_32x32x16_bf16 v[96:111], v[184:187], v[148:151], v[48:63]
	v_add_f32_e32 v2, v86, v2
	v_add_f32_e32 v2, v87, v2
	v_add_f32_e32 v2, v88, v2
	v_add_f32_e32 v2, v89, v2
	v_cvt_pk_bf16_f32 v158, v84, v85
	v_cvt_pk_bf16_f32 v159, v86, v87
	ds_read_b64_tr_b16 v[184:185], v0 offset:25600
	ds_read_b64_tr_b16 v[186:187], v0 offset:26112
	v_mfma_f32_32x32x16_bf16 v[112:127], v[180:183], v[140:143], v[112:127]
	v_add_f32_e32 v2, v90, v2
	v_add_f32_e32 v2, v91, v2
	v_add_f32_e32 v2, v92, v2
	v_add_f32_e32 v2, v93, v2
	v_cvt_pk_bf16_f32 v152, v88, v89
	v_cvt_pk_bf16_f32 v153, v90, v91
	ds_read_b64_tr_b16 v[84:85], v0 offset:29696
	ds_read_b64_tr_b16 v[86:87], v0 offset:30208
	v_mfma_f32_32x32x16_bf16 v[96:111], v[176:179], v[140:143], v[96:111]
	v_add_f32_e32 v2, v94, v2
	v_add_f32_e32 v2, v95, v2
	v_add_f32_e32 v2, v64, v2
	v_add_f32_e32 v2, v65, v2
	v_cvt_pk_bf16_f32 v154, v92, v93
	v_cvt_pk_bf16_f32 v155, v94, v95
	ds_read_b64_tr_b16 v[80:81], v0 offset:26624
	ds_read_b64_tr_b16 v[82:83], v0 offset:27136
	v_mfma_f32_32x32x16_bf16 v[112:127], v[172:175], v[132:135], v[112:127]
	v_add_f32_e32 v2, v66, v2
	v_add_f32_e32 v2, v67, v2
	v_add_f32_e32 v2, v68, v2
	v_add_f32_e32 v2, v69, v2
	v_cvt_pk_bf16_f32 v144, v64, v65
	v_cvt_pk_bf16_f32 v145, v66, v67
	ds_read_b64_tr_b16 v[10:11], v0 offset:30720
	ds_read_b64_tr_b16 v[12:13], v0 offset:31232
	v_mfma_f32_32x32x16_bf16 v[96:111], v[168:171], v[132:135], v[96:111]
	v_add_f32_e32 v2, v70, v2
	v_add_f32_e32 v2, v71, v2
	v_add_f32_e32 v2, v72, v2
	v_add_f32_e32 v2, v73, v2
	v_cvt_pk_bf16_f32 v146, v68, v69
	v_cvt_pk_bf16_f32 v147, v70, v71
	ds_read_b64_tr_b16 v[6:7], v0 offset:27648
	ds_read_b64_tr_b16 v[8:9], v0 offset:28160
	v_mfma_f32_32x32x16_bf16 v[112:127], v[164:167], v[128:131], v[112:127]
	v_add_f32_e32 v2, v74, v2
	v_add_f32_e32 v2, v75, v2
	v_add_f32_e32 v2, v76, v2
	v_add_f32_e32 v14, v77, v2
	v_cvt_pk_bf16_f32 v136, v72, v73
	v_cvt_pk_bf16_f32 v137, v74, v75
	ds_read_b64_tr_b16 v[2:3], v0 offset:31744
	ds_read_b64_tr_b16 v[4:5], v0 offset:32256
	v_mfma_f32_32x32x16_bf16 v[96:111], v[160:163], v[128:131], v[96:111]
	v_add_f32_e32 v0, v78, v14
	v_add_f32_e32 v0, v79, v0
	v_cvt_pk_bf16_f32 v138, v76, v77
	v_cvt_pk_bf16_f32 v139, v78, v79
	v_lshl_add_u64 v[14:15], v[202:203], 0, s[26:27]
	s_add_i32 s8, s40, s46
	s_mov_b32 s9, m0
	s_mov_b32 m0, s8
	s_nop 0
	global_load_lds_dwordx4 v[14:15], off
	s_mov_b32 m0, s9
	v_lshl_add_u64 v[14:15], v[200:201], 0, s[26:27]
	s_add_i32 s8, s38, s47
	s_mov_b32 s9, m0
	s_mov_b32 m0, s8
	s_nop 0
	global_load_lds_dwordx4 v[14:15], off
	s_mov_b32 m0, s9
	v_max3_f32 v14, v112, v113, v114
	v_max3_f32 v15, v115, v116, v117
	v_max3_f32 v14, v14, v118, v119
	v_max3_f32 v15, v15, v120, v121
	v_max3_f32 v14, v14, v122, v123
	v_max3_f32 v15, v15, v124, v125
	v_max3_f32 v14, v14, v126, v127
	v_max3_f32 v15, v15, v96, v97
	v_max3_f32 v14, v14, v98, v99
	v_max3_f32 v15, v15, v100, v101
	v_max3_f32 v14, v14, v102, v103
	v_max3_f32 v15, v15, v104, v105
	v_max3_f32 v14, v14, v106, v107
	v_max3_f32 v15, v15, v108, v109
	v_max3_f32 v64, v14, v110, v111
	v_add_f32_e32 v14, v223, v0
	v_max_f32_e32 v0, v64, v15
	v_mov_b32_e32 v15, v0
	s_nop 1
	v_permlane32_swap_b32_e32 v0, v15
	v_max_f32_e32 v0, v0, v15
	v_cmp_lt_f32_e32 vcc, s53, v0
	s_cmp_lg_u64 vcc, 0
	s_cselect_b64 s[8:9], -1, 0
	s_cbranch_vccnz .LBB0_1555

.LBB0_1550:
	s_add_i32 s8, s38, 0x2000
	s_cmpk_lg_i32 s38, 0x4000
	s_cselect_b32 s13, s8, 0
	v_add_u32_e32 v4, s40, v221
	ds_read_b64_tr_b16 v[168:169], v4 offset:24576
	ds_read_b64_tr_b16 v[170:171], v4 offset:25088
	v_mfma_f32_32x32x16_bf16 v[80:95], v[64:67], v[148:151], v[48:63]
	v_add_f32_e32 v2, v112, v113
	v_add_f32_e32 v2, v114, v2
	v_add_f32_e32 v2, v115, v2
	v_add_f32_e32 v2, v116, v2
	v_add_f32_e32 v2, v117, v2
	v_cvt_pk_bf16_f32 v156, v112, v113
	v_cvt_pk_bf16_f32 v157, v114, v115
	ds_read_b64_tr_b16 v[164:165], v4 offset:28672
	ds_read_b64_tr_b16 v[166:167], v4 offset:29184
	v_mfma_f32_32x32x16_bf16 v[64:79], v[160:163], v[148:151], v[48:63]
	v_add_f32_e32 v2, v118, v2
	v_add_f32_e32 v2, v119, v2
	v_add_f32_e32 v2, v120, v2
	v_add_f32_e32 v2, v121, v2
	v_cvt_pk_bf16_f32 v158, v116, v117
	v_cvt_pk_bf16_f32 v159, v118, v119
	ds_read_b64_tr_b16 v[160:161], v4 offset:25600
	ds_read_b64_tr_b16 v[162:163], v4 offset:26112
	v_mfma_f32_32x32x16_bf16 v[80:95], v[192:195], v[140:143], v[80:95]
	v_add_f32_e32 v2, v122, v2
	v_add_f32_e32 v2, v123, v2
	v_add_f32_e32 v2, v124, v2
	v_add_f32_e32 v2, v125, v2
	v_cvt_pk_bf16_f32 v152, v120, v121
	v_cvt_pk_bf16_f32 v153, v122, v123
	ds_read_b64_tr_b16 v[116:117], v4 offset:29696
	ds_read_b64_tr_b16 v[118:119], v4 offset:30208
	v_mfma_f32_32x32x16_bf16 v[64:79], v[184:187], v[140:143], v[64:79]
	v_add_f32_e32 v2, v126, v2
	v_add_f32_e32 v2, v127, v2
	v_add_f32_e32 v2, v96, v2
	v_add_f32_e32 v2, v97, v2
	v_cvt_pk_bf16_f32 v154, v124, v125
	v_cvt_pk_bf16_f32 v155, v126, v127
	ds_read_b64_tr_b16 v[112:113], v4 offset:26624
	ds_read_b64_tr_b16 v[114:115], v4 offset:27136
	v_mfma_f32_32x32x16_bf16 v[80:95], v[188:191], v[132:135], v[80:95]
	v_add_f32_e32 v2, v98, v2
	v_add_f32_e32 v2, v99, v2
	v_add_f32_e32 v2, v100, v2
	v_add_f32_e32 v2, v101, v2
	v_cvt_pk_bf16_f32 v144, v96, v97
	v_cvt_pk_bf16_f32 v145, v98, v99
	ds_read_b64_tr_b16 v[10:11], v4 offset:30720
	ds_read_b64_tr_b16 v[12:13], v4 offset:31232
	v_mfma_f32_32x32x16_bf16 v[64:79], v[176:179], v[132:135], v[64:79]
	v_add_f32_e32 v2, v102, v2
	v_add_f32_e32 v2, v103, v2
	v_add_f32_e32 v2, v104, v2
	v_add_f32_e32 v2, v105, v2
	v_cvt_pk_bf16_f32 v146, v100, v101
	v_cvt_pk_bf16_f32 v147, v102, v103
	ds_read_b64_tr_b16 v[6:7], v4 offset:27648
	ds_read_b64_tr_b16 v[8:9], v4 offset:28160
	v_mfma_f32_32x32x16_bf16 v[80:95], v[180:183], v[128:131], v[80:95]
	v_add_f32_e32 v2, v106, v2
	v_add_f32_e32 v2, v107, v2
	v_add_f32_e32 v2, v108, v2
	v_add_f32_e32 v15, v109, v2
	v_cvt_pk_bf16_f32 v136, v104, v105
	v_cvt_pk_bf16_f32 v137, v106, v107
	ds_read_b64_tr_b16 v[2:3], v4 offset:31744
	ds_read_b64_tr_b16 v[4:5], v4 offset:32256
	v_mfma_f32_32x32x16_bf16 v[64:79], v[172:175], v[128:131], v[64:79]
	v_add_f32_e32 v15, v110, v15
	v_add_f32_e32 v15, v111, v15
	v_cvt_pk_bf16_f32 v138, v108, v109
	v_cvt_pk_bf16_f32 v139, v110, v111
	v_max3_f32 v96, v80, v81, v82
	v_max3_f32 v97, v83, v84, v85
	v_max3_f32 v96, v96, v86, v87
	v_max3_f32 v97, v97, v88, v89
	v_max3_f32 v96, v96, v90, v91
	v_max3_f32 v97, v97, v92, v93
	v_max3_f32 v96, v96, v94, v95
	v_add_f32_e32 v223, v14, v15
	s_nop 0
	v_max3_f32 v97, v97, v64, v65
	v_max3_f32 v96, v96, v66, v67
	v_max3_f32 v97, v97, v68, v69
	v_max3_f32 v96, v96, v70, v71
	v_max3_f32 v97, v97, v72, v73
	v_max3_f32 v96, v96, v74, v75
	v_max3_f32 v97, v97, v76, v77
	v_max3_f32 v96, v96, v78, v79
	v_max_f32_e32 v14, v96, v97
	v_mov_b32_e32 v15, v14
	s_nop 1
	v_permlane32_swap_b32_e32 v14, v15
	s_add_i32 s8, s38, s46
	s_mov_b32 s9, m0
	s_mov_b32 m0, s8
	s_nop 0
	global_load_lds_dwordx4 v[202:203], off
	s_mov_b32 m0, s9
	v_max_f32_e32 v14, v14, v15
	s_add_i32 s8, s13, s47
	s_mov_b32 s9, m0
	s_mov_b32 m0, s8
	s_nop 0
	global_load_lds_dwordx4 v[200:201], off
	s_mov_b32 m0, s9
	v_cmp_lt_f32_e32 vcc, s53, v14
	s_cmp_lg_u64 vcc, 0
	s_cselect_b64 s[8:9], -1, 0
	s_cbranch_vccnz .LBB0_1558
